# sliding-window layer: attention units remapped to the row-block owner group; qkv->attn = own + previous-block group wait, attn->out-proj = group wait; LN1->up checks every group left attention (overla
# baseline (speedup 1.0000x reference)
.LBB0_1321:
	v_readlane_b32 s0, v253, 37
	v_readlane_b32 s16, v250, 0
	s_or_b32 s0, s0, 3
	v_readlane_b32 s19, v250, 3
	s_cmp_ge_i32 s0, s19
	v_readlane_b32 s17, v250, 1
	v_readlane_b32 s18, v250, 2
	s_cbranch_scc1 .LBB0_1377
	s_waitcnt vmcnt(0)
	v_readlane_b32 s2, v253, 40
	v_readlane_b32 s3, v253, 41
	s_and_b64 vcc, exec, s[2:3]
	s_waitcnt vmcnt(0) lgkmcnt(0)
	s_barrier
	s_cbranch_vccnz .LBB0_1376
	s_mov_b32 s2, -1
	s_nop 0
	v_mbcnt_lo_u32_b32 v0, s2, 0
	v_mbcnt_hi_u32_b32 v0, s2, v0
	s_nop 0
	v_cmp_eq_u32_e32 vcc, 0, v0
	s_and_saveexec_b64 s[16:17], vcc
	s_cbranch_execz .LBB0_1375
	s_cmp_lg_u32 s101, 1
	s_cbranch_scc1 .Lmy_gfull_10
	v_readlane_b32 s2, v253, 37
	v_readlane_b32 s3, v250, 7
	v_readlane_b32 s8, v250, 0
	v_readlane_b32 s9, v250, 1
	s_lshl_b32 s2, s2, 12
	s_add_i32 s2, s2, 0xa000
	s_add_u32 s8, s8, 0x70000
	s_addc_u32 s9, s9, 0
	s_and_b32 s12, s3, 7
	s_lshl_b32 s12, s12, 3
	s_bfe_u32 s13, s3, 0x30003
	s_or_b32 s12, s12, s13
	s_and_b32 s13, s12, 7
	s_cmp_lg_u32 s13, 7
	s_cbranch_scc1 .Lmy_g10_nowb
	s_and_b32 s13, s12, 31
	s_cmp_eq_u32 s13, 31
	s_cbranch_scc1 .Lmy_g10_nowb
	s_waitcnt vmcnt(0) lgkmcnt(0)
	buffer_wbl2 sc1
	s_waitcnt vmcnt(0)

.LBB0_1381:
	s_mov_b32 s98, s28
	s_cmp_lg_u32 s94, 0x100
	s_cbranch_scc1 .Lmy_swamap
	v_readlane_b32 s99, v250, 7
	s_and_b32 s98, s99, 7
	s_lshl_b32 s98, s98, 3
	s_bfe_u32 s0, s99, 0x30003
	s_or_b32 s98, s98, s0
	s_lshr_b32 s0, s28, 8
	s_lshl_b32 s98, s98, 1
	s_or_b32 s98, s98, s0
	s_lshl_b32 s98, s98, 2
	s_lshr_b32 s99, s99, 6
	s_or_b32 s98, s98, s99
.Lmy_swamap:
	s_bfe_u32 s0, s98, 0x60002
	s_lshl_b32 s2, s98, 5
	s_and_b32 s7, s2, 0xffffe000
	s_lshl_b32 s2, s0, 7
	s_or_b32 s2, s2, s7
	s_add_i32 s12, s2, 0xffffff80
	v_add_u32_e32 v0, s12, v103
	s_and_b32 s3, s98, 3
	v_max_i32_e32 v0, s7, v0
	v_mov_b64_e32 v[4:5], s[20:21]
	s_movk_i32 s22, 0x1400
	v_mad_i64_i32 v[0:1], s[8:9], v0, s22, v[4:5]
	s_lshl_b32 s10, s3, 7
	v_lshl_add_u64 v[0:1], v[0:1], 0, s[10:11]
	v_lshl_add_u64 v[0:1], v[0:1], 0, v[224:225]
	s_movk_i32 s13, 0x1000
	v_add_co_u32_e32 v0, vcc, s13, v0
	s_waitcnt vmcnt(0)
	s_nop 0
	v_addc_co_u32_e32 v1, vcc, 0, v1, vcc
	s_barrier
	global_load_dwordx4 v[200:203], v[0:1], off
	s_movk_i32 s33, 0x1400
	s_lshl_b32 s3, s3, 3
	v_add_u32_e32 v0, s12, v125
	v_max_i32_e32 v0, s7, v0
	v_mad_i64_i32 v[0:1], s[8:9], v0, s22, v[4:5]
	v_lshl_add_u64 v[0:1], v[0:1], 0, s[10:11]
	v_lshl_add_u64 v[0:1], v[0:1], 0, v[224:225]
	v_add_co_u32_e32 v0, vcc, s13, v0
	s_nop 1
	v_addc_co_u32_e32 v1, vcc, 0, v1, vcc
	global_load_dwordx4 v[204:207], v[0:1], off
	v_add_u32_e32 v0, s12, v126
	v_max_i32_e32 v0, s7, v0
	v_mad_i64_i32 v[0:1], s[8:9], v0, s22, v[4:5]
	v_lshl_add_u64 v[0:1], v[0:1], 0, s[10:11]
	v_lshl_add_u64 v[0:1], v[0:1], 0, v[224:225]
	v_add_co_u32_e32 v0, vcc, s13, v0
	s_nop 1
	v_addc_co_u32_e32 v1, vcc, 0, v1, vcc
	global_load_dwordx4 v[208:211], v[0:1], off
	v_add_u32_e32 v0, s12, v127
	v_max_i32_e32 v0, s7, v0
	v_mad_i64_i32 v[0:1], s[8:9], v0, s22, v[4:5]
	v_lshl_add_u64 v[0:1], v[0:1], 0, s[10:11]
	v_lshl_add_u64 v[0:1], v[0:1], 0, v[224:225]
	v_add_co_u32_e32 v0, vcc, s13, v0
	s_nop 1
	v_addc_co_u32_e32 v1, vcc, 0, v1, vcc
	global_load_dwordx4 v[212:215], v[0:1], off
	v_add_u32_e32 v0, s12, v101
	v_max_i32_e32 v0, s7, v0
	v_mad_i64_i32 v[0:1], s[8:9], v0, s22, v[4:5]
	v_lshl_add_u64 v[0:1], v[0:1], 0, s[10:11]
	s_mov_b64 s[8:9], 0x1200
	v_lshl_add_u64 v[4:5], v[0:1], 0, s[8:9]
	v_lshl_add_u64 v[0:1], v[106:107], 1, v[4:5]
	global_load_dwordx4 v[216:219], v[0:1], off
	v_lshl_add_u64 v[0:1], v[108:109], 1, v[4:5]
	global_load_dwordx4 v[220:223], v[0:1], off
	v_lshl_add_u64 v[0:1], v[110:111], 1, v[4:5]
	global_load_dwordx4 v[226:229], v[0:1], off
	v_lshl_add_u64 v[0:1], v[112:113], 1, v[4:5]
	global_load_dwordx4 v[230:233], v[0:1], off
	s_waitcnt vmcnt(7)
	ds_write_b128 v157, v[200:203]
	s_waitcnt vmcnt(6)
	ds_write_b128 v158, v[204:207]
	s_waitcnt vmcnt(5)
	ds_write_b128 v159, v[208:211]
	s_waitcnt vmcnt(4)
	ds_write_b128 v160, v[212:215]
	s_waitcnt vmcnt(3)
	ds_write_b16 v161, v216 offset:36864
	ds_write_b16_d16_hi v161, v216 offset:37392
	ds_write_b16 v161, v217 offset:37920
	ds_write_b16_d16_hi v161, v217 offset:38448
	ds_write_b16 v161, v218 offset:38976
	ds_write_b16_d16_hi v161, v218 offset:39504
	ds_write_b16 v161, v219 offset:40032
	ds_write_b16_d16_hi v162, v219 offset:36864
	s_waitcnt vmcnt(2)
	ds_write_b16 v163, v220 offset:36864
	ds_write_b16_d16_hi v163, v220 offset:37392
	ds_write_b16 v163, v221 offset:37920
	ds_write_b16_d16_hi v163, v221 offset:38448
	ds_write_b16 v163, v222 offset:38976
	ds_write_b16_d16_hi v163, v222 offset:39504
	ds_write_b16 v163, v223 offset:40032
	ds_write_b16_d16_hi v164, v223 offset:36864
	s_waitcnt vmcnt(1)
	ds_write_b16 v165, v226 offset:36864
	ds_write_b16_d16_hi v165, v226 offset:37392
	ds_write_b16 v165, v227 offset:37920
	ds_write_b16_d16_hi v165, v227 offset:38448
	ds_write_b16 v165, v228 offset:38976
	ds_write_b16_d16_hi v165, v228 offset:39504
	ds_write_b16 v165, v229 offset:40032
	ds_write_b16_d16_hi v166, v229 offset:36864
	s_waitcnt vmcnt(0)
	ds_write_b16 v167, v230 offset:36864
	ds_write_b16_d16_hi v167, v230 offset:37392
	ds_write_b16 v167, v231 offset:37920
	ds_write_b16_d16_hi v167, v231 offset:38448
	ds_write_b16 v167, v232 offset:38976
	ds_write_b16_d16_hi v167, v232 offset:39504
	ds_write_b16 v167, v233 offset:40032
	ds_write_b16_d16_hi v168, v233 offset:36864
	s_and_saveexec_b64 s[8:9], s[38:39]
	s_cbranch_execz .LBB0_1389
	global_load_ubyte v0, v[114:115], off
	s_mov_b64 s[22:23], -1
	v_mov_b32_e32 v1, v96
	s_waitcnt vmcnt(0)
	v_lshl_or_b32 v0, v0, 5, s3
	s_and_saveexec_b64 s[12:13], s[66:67]
	s_cbranch_execz .LBB0_1386
	v_mov_b32_e32 v1, v0
	s_mov_b64 s[22:23], 0
	v_mov_b32_e32 v4, v141
	v_mov_b32_e32 v5, v156
	v_mov_b64_e32 v[2:3], v[96:97]

.LBB0_1551:
	v_readlane_b32 s0, v253, 37
	v_readlane_b32 s16, v250, 0
	s_or_b32 s0, s0, 4
	v_readlane_b32 s19, v250, 3
	v_readlane_b32 s68, v253, 19
	s_cmp_ge_i32 s0, s19
	v_readlane_b32 s67, v253, 10
	v_readlane_b32 s69, v253, 20
	v_readlane_b32 s64, v253, 21
	v_readlane_b32 s63, v253, 24
	v_readlane_b32 s66, v253, 25
	s_mov_b32 s53, 0x5040100
	s_mov_b64 s[56:57], 0x400000
	s_mov_b64 s[58:59], 0x3fffff
	s_mov_b64 s[60:61], 0x20000
	v_readlane_b32 s48, v253, 35
	v_readlane_b32 s17, v250, 1
	v_readlane_b32 s18, v250, 2
	v_readlane_b32 s65, v253, 22
	v_readlane_b32 s49, v253, 36
	s_cbranch_scc1 .LBB0_1607
	s_waitcnt vmcnt(0)
	v_readlane_b32 s2, v253, 40
	v_readlane_b32 s3, v253, 41
	s_and_b64 vcc, exec, s[2:3]
	s_waitcnt vmcnt(0)
	s_barrier
	s_cbranch_vccnz .LBB0_1606
	s_cmp_lg_u32 s101, 0
	s_cbranch_scc1 .Lmy_gchk_11
	s_mov_b32 s101, 2
	s_cmp_lg_u32 s94, 0x100
	s_cbranch_scc1 .Lmy_gchk_11
	v_readlane_b32 s8, v250, 0
	v_readlane_b32 s9, v250, 1
	s_mov_b32 s2, -1
	v_mbcnt_lo_u32_b32 v0, s2, 0
	v_mbcnt_hi_u32_b32 v0, s2, v0
	v_lshlrev_b32_e32 v0, 2, v0
	s_add_u32 s8, s8, 0x60000
	s_addc_u32 s9, s9, 0
	global_load_dword v1, v0, s[8:9] sc0 sc1
	global_load_dword v2, v0, s[8:9] offset:256 sc0 sc1
	global_load_dword v3, v0, s[8:9] offset:512 sc0 sc1
	global_load_dword v4, v0, s[8:9] offset:768 sc0 sc1
	v_and_b32_e32 v5, 28, v0
	global_load_dword v5, v5, s[8:9] sc0 sc1
	s_waitcnt vmcnt(0)
	v_cmp_eq_u32_e64 s[12:13], v1, v5
	s_nop 1
	v_cmp_ne_u32_e32 vcc, 0, v1
	v_cmp_eq_u32_e64 s[2:3], v1, v2
	s_and_b64 s[2:3], s[2:3], s[12:13]
	v_cmp_eq_u32_e64 s[12:13], v1, v3
	s_and_b64 s[2:3], s[2:3], vcc
	v_cmp_eq_u32_e64 s[8:9], v1, v4
	s_and_b64 s[2:3], s[2:3], s[12:13]
	s_and_b64 s[2:3], s[2:3], s[8:9]
	s_cmp_eq_u64 s[2:3], -1
	s_cbranch_scc0 .Lmy_gchk_11
	s_mov_b32 s101, 1
.Lmy_gchk_11:
	s_mov_b32 s0, -1
	s_nop 0
	v_mbcnt_lo_u32_b32 v0, s0, 0
	v_mbcnt_hi_u32_b32 v0, s0, v0
	s_nop 0
	v_cmp_eq_u32_e32 vcc, 0, v0
	s_and_saveexec_b64 s[16:17], vcc
	s_cbranch_execz .LBB0_1605
	s_cmp_lg_u32 s101, 1
	s_cbranch_scc1 .Lmy_gfull_11
	v_readlane_b32 s2, v253, 37
	v_readlane_b32 s3, v250, 7
	v_readlane_b32 s8, v250, 0
	v_readlane_b32 s9, v250, 1
	s_lshl_b32 s2, s2, 12
	s_add_i32 s2, s2, 0xb000
	s_and_b32 s3, s3, 63
	s_lshl_b32 s3, s3, 6
	s_add_i32 s2, s2, s3
	s_add_u32 s8, s8, 0x70000
	s_addc_u32 s9, s9, 0
	v_mov_b32_e32 v0, s2
	v_mov_b32_e32 v1, 1
	s_waitcnt vmcnt(0) lgkmcnt(0)
	global_atomic_add v0, v1, s[8:9]
	s_mov_b32 s2, 0

.Lmy_g3_own:
	s_cmp_eq_u32 s100, 32
	s_cbranch_scc1 .Lmy_g3_all
	s_cmp_lg_u32 s100, 16
	s_cbranch_scc1 .Lmy_gdone_3
	s_add_i32 s12, s12, 0xb000
.Lmy_g3_all:
	s_mov_b64 exec, -1
	s_mov_b32 s2, -1
	v_mbcnt_lo_u32_b32 v0, s2, 0
	v_mbcnt_hi_u32_b32 v0, s2, v0
	v_lshlrev_b32_e32 v0, 6, v0
	v_add_u32_e32 v0, s12, v0
	s_mov_b32 s100, 0
